# spatial gating loop: second row-block's U/bias loads hoisted to the unit top into fresh registers, next unit's V^T loads issued after them, counted vmcnt waits instead of two full drains; on top of v2
# baseline (speedup 1.0000x reference)
; #define LAS __attribute__((address_space(3)))
; #define GAS __attribute__((address_space(1)))
; #define SP_VLOAD(unit_, raw_) do { const bf16_t* vp = VT + (size_t)(((unit_) & 7) * 128 + r4) * ldt + ((unit_) >> 3) * 128 + sbase; \
;         _Pragma("unroll") for (int c = 0; c < 4; ++c) raw_[c] = *(const GAS u32x4*)(vp + 8 * c); } while (0)
; __device__ __forceinline__ void spatial_phase(LAS unsigned char* lds, const bf16_t* U, const bf16_t* VT, const float* vsum, const float* vsq, const float* lng, const float* Ws, const float* bs, bf16_t* Y, int c0, int G, int nunits, int ldt) {
;     ...
;     for (int unit = c0; unit < nunits; unit += G, ++it) {
;         const int cur = it & 1, nxt = cur ^ 1, un = unit + G, un2 = unit + 2 * G;
;         const int bc = unit >> 3, g = unit & 7, tok0 = bc * 128, ch0 = g * 128;
;         if (un < nunits) SP_VLOAD(un, vraw);
;         const LAS unsigned char* Vc = Vl + cur * 32768;
; #pragma unroll
;         for (int ti = 0; ti < 2; ++ti) {
;             const int tt = 2 * tp + ti, brow = tt * 32 + q, bswz = brow & 15, nks = 2 * (tt + 1);
;             const float bias = bs[g * 128 + tt * 32 + q];
;             const size_t off = (size_t)(tok0 + tt * 32 + q) * DM + ch0 + ct * 32 + 16 * hh;
;             const u32x4 ua = *(const GAS u32x4*)(U + off), ub = *(const GAS u32x4*)(U + off + 8);
.LBB0_250:
	s_lshl_b32 s0, s78, 4
	s_and_b32 s8, s0, 0xffffff80
	s_lshl_b32 s0, s78, 7
	s_and_b32 s0, s0, 0x380
	v_or_b32_e32 v71, s0, v60
	v_add_u32_e32 v0, s51, v71
	v_ashrrev_i32_e32 v1, 31, v0
	v_or_b32_e32 v70, s8, v60
	v_lshl_add_u64 v[0:1], v[0:1], 2, s[82:83]
	global_load_dword v72, v[0:1], off
	v_add_u32_e32 v0, s51, v70
	v_ashrrev_i32_e32 v1, 31, v0
	v_or_b32_e32 v69, s0, v64
	v_lshlrev_b64 v[48:49], 10, v[0:1]
	v_or_b32_e32 v48, v48, v69
	v_lshl_add_u64 v[0:1], v[48:49], 1, s[40:41]
	global_load_dwordx4 v[34:37], v[0:1], off offset:16
	global_load_dwordx4 v[38:41], v[0:1], off
	v_add_u32_e32 v208, s84, v71
	v_ashrrev_i32_e32 v209, 31, v208
	v_lshl_add_u64 v[208:209], v[208:209], 2, s[82:83]
	global_load_dword v205, v[208:209], off
	v_add_u32_e32 v208, s84, v70
	v_ashrrev_i32_e32 v209, 31, v208
	v_lshlrev_b64 v[206:207], 10, v[208:209]
	v_or_b32_e32 v206, v206, v69
	v_lshl_add_u64 v[208:209], v[206:207], 1, s[40:41]
	global_load_dwordx4 v[196:199], v[208:209], off offset:16
	global_load_dwordx4 v[200:203], v[208:209], off
	s_and_b64 vcc, exec, s[46:47]
	s_cbranch_vccnz .Lsp_novl
	s_lshl_b32 s100, s87, 7
	s_and_b32 s100, s100, 0x380
	v_add_u32_e32 v0, s100, v42
	v_ashrrev_i32_e32 v1, 31, v0
	v_readlane_b32 s100, v253, 2
	v_readlane_b32 s8, v254, 33
	v_readlane_b32 s9, v254, 34
	v_lshlrev_b64 v[0:1], s100, v[0:1]
	s_lshl_b32 s100, s87, 4
	v_lshl_add_u64 v[0:1], v[0:1], 1, s[8:9]
	s_and_b32 s8, s100, 0xffffff80
	s_ashr_i32 s9, s8, 31
	v_lshl_add_u64 v[0:1], s[8:9], 1, v[0:1]
	v_mov_b32_e32 v45, v32
	v_lshl_add_u64 v[0:1], v[0:1], 0, v[44:45]
	global_load_dwordx4 v[16:19], v[0:1], off offset:48
	global_load_dwordx4 v[20:23], v[0:1], off offset:32
	global_load_dwordx4 v[24:27], v[0:1], off offset:16
	global_load_dwordx4 v[28:31], v[0:1], off
.Lsp_novl:
	s_and_b32 s78, s85, 1
	v_cndmask_b32_e64 v0, 0, 1, s[44:45]
	v_cmp_ne_u32_e64 s[8:9], 1, v0
	s_andn2_b64 vcc, exec, s[44:45]
	v_lshl_add_u32 v45, s78, 15, v65
	s_cbranch_vccnz .LBB0_253
	v_mov_b32_e32 v0, 0
	v_mov_b32_e32 v73, v61
	s_mov_b32 s80, s79
	v_mov_b32_e32 v1, v0
	v_mov_b32_e32 v2, v0
	v_mov_b32_e32 v3, v0
	v_mov_b32_e32 v4, v0
	v_mov_b32_e32 v5, v0
	v_mov_b32_e32 v6, v0
	v_mov_b32_e32 v7, v0
	v_mov_b32_e32 v8, v0
	v_mov_b32_e32 v9, v0
	v_mov_b32_e32 v10, v0
	v_mov_b32_e32 v11, v0
	v_mov_b32_e32 v12, v0
	v_mov_b32_e32 v13, v0
	v_mov_b32_e32 v14, v0
	v_mov_b32_e32 v15, v0

; __device__ __forceinline__ unsigned cvt_pk_bf16(float lo, float hi) { unsigned r; asm volatile("v_cvt_pk_bf16_f32 %0, %1, %2" : "=v"(r) : "v"(lo), "v"(hi)); return r; }
; #define GAS __attribute__((address_space(1)))
; __device__ __forceinline__ float bf_lo(unsigned w) { return __uint_as_float(w << 16); }
; __device__ __forceinline__ float bf_hi(unsigned w) { return __uint_as_float(w & 0xffff0000u); }
; __device__ __forceinline__ void spatial_phase(LAS unsigned char* lds, const bf16_t* U, const bf16_t* VT, const float* vsum, const float* vsq, const float* lng, const float* Ws, const float* bs, bf16_t* Y, int c0, int G, int nunits, int ldt) {
;     ...
;             f32x16 C;
; #pragma unroll
;             for (int r = 0; r < 16; ++r) C[r] = 0.f;
;             for (int ks = 0; ks < nks; ++ks) { const int chunk = 2 * ks + hh;
;                 const bf16x8 A = lds_frag(Vc + arow * 256 + ((chunk ^ aswz) << 4)), B = lds_frag(Wl + brow * 256 + ((chunk ^ bswz) << 4));
;                 C = __builtin_amdgcn_mfma_f32_32x32x16_bf16(A, B, C, 0, 0, 0); }
;             u32x4 oa, ob;
;             oa.x = cvt_pk_bf16(bf_lo(ua.x) * (C[0] + bias), bf_hi(ua.x) * (C[1] + bias)); oa.y = cvt_pk_bf16(bf_lo(ua.y) * (C[2] + bias), bf_hi(ua.y) * (C[3] + bias));
;             oa.z = cvt_pk_bf16(bf_lo(ua.z) * (C[4] + bias), bf_hi(ua.z) * (C[5] + bias)); oa.w = cvt_pk_bf16(bf_lo(ua.w) * (C[6] + bias), bf_hi(ua.w) * (C[7] + bias));
;             ob.x = cvt_pk_bf16(bf_lo(ub.x) * (C[8] + bias), bf_hi(ub.x) * (C[9] + bias)); ob.y = cvt_pk_bf16(bf_lo(ub.y) * (C[10] + bias), bf_hi(ub.y) * (C[11] + bias));
;             ob.z = cvt_pk_bf16(bf_lo(ub.z) * (C[12] + bias), bf_hi(ub.z) * (C[13] + bias)); ob.w = cvt_pk_bf16(bf_lo(ub.w) * (C[14] + bias), bf_hi(ub.w) * (C[15] + bias));
;             *(GAS u32x4*)(Y + off) = oa; *(GAS u32x4*)(Y + off + 8) = ob;
.LBB0_254:
	s_waitcnt vmcnt(7)
	s_cmp_eq_u32 s46, 0
	s_cbranch_scc1 .Lsp_w0
	s_waitcnt vmcnt(3)
.Lsp_w0:
	v_lshlrev_b32_e32 v73, 16, v38
	s_nop 7
	v_add_f32_e32 v0, v72, v0
	v_and_b32_e32 v38, 0xffff0000, v38
	v_add_f32_e32 v1, v72, v1
	v_mul_f32_e32 v0, v0, v73
	v_mul_f32_e32 v1, v1, v38
	v_cvt_pk_bf16_f32 v0, v0, v1
	v_lshlrev_b32_e32 v1, 16, v39
	v_add_f32_e32 v2, v72, v2
	v_mul_f32_e32 v1, v2, v1
	v_and_b32_e32 v2, 0xffff0000, v39
	v_add_f32_e32 v3, v72, v3
	v_mul_f32_e32 v2, v3, v2
	v_cvt_pk_bf16_f32 v1, v1, v2
	v_lshlrev_b32_e32 v2, 16, v40
	v_add_f32_e32 v3, v72, v4
	v_mul_f32_e32 v2, v3, v2
	v_and_b32_e32 v3, 0xffff0000, v40
	v_add_f32_e32 v4, v72, v5
	v_mul_f32_e32 v3, v4, v3
	v_cvt_pk_bf16_f32 v2, v2, v3
	v_lshlrev_b32_e32 v3, 16, v41
	v_add_f32_e32 v4, v72, v6
	v_mul_f32_e32 v3, v4, v3
	v_and_b32_e32 v4, 0xffff0000, v41
	v_add_f32_e32 v5, v72, v7
	v_mul_f32_e32 v4, v5, v4
	v_cvt_pk_bf16_f32 v3, v3, v4
	v_lshlrev_b32_e32 v4, 16, v34
	v_add_f32_e32 v5, v72, v8
	v_mul_f32_e32 v4, v5, v4
	v_and_b32_e32 v5, 0xffff0000, v34
	v_add_f32_e32 v6, v72, v9
	v_mul_f32_e32 v5, v6, v5
	v_cvt_pk_bf16_f32 v4, v4, v5
	v_lshlrev_b32_e32 v5, 16, v35
	v_add_f32_e32 v6, v72, v10
	v_mul_f32_e32 v5, v6, v5
	v_and_b32_e32 v6, 0xffff0000, v35
	v_add_f32_e32 v7, v72, v11
	v_mul_f32_e32 v6, v7, v6
	v_cvt_pk_bf16_f32 v5, v5, v6
	v_lshlrev_b32_e32 v6, 16, v36
	v_add_f32_e32 v7, v72, v12
	v_mul_f32_e32 v6, v7, v6
	v_and_b32_e32 v7, 0xffff0000, v36
	v_add_f32_e32 v8, v72, v13
	v_mul_f32_e32 v7, v8, v7
	v_cvt_pk_bf16_f32 v6, v6, v7
	v_lshlrev_b32_e32 v7, 16, v37
	v_add_f32_e32 v8, v72, v14
	v_mul_f32_e32 v7, v8, v7
	v_and_b32_e32 v8, 0xffff0000, v37
	v_add_f32_e32 v9, v72, v15
	v_readlane_b32 s88, v252, 1
	v_mul_f32_e32 v8, v9, v8
	v_readlane_b32 s90, v252, 3
	v_readlane_b32 s91, v252, 4
	v_cvt_pk_bf16_f32 v7, v7, v8
	s_and_b64 vcc, exec, s[8:9]
	v_readlane_b32 s89, v252, 2
	v_lshl_add_u64 v[8:9], v[48:49], 1, s[90:91]
	global_store_dwordx4 v[8:9], v[0:3], off
	global_store_dwordx4 v[8:9], v[4:7], off offset:16
	s_nop 0
	s_cbranch_vccnz .LBB0_257
	v_mov_b32_e32 v0, 0
	v_mov_b32_e32 v69, v61
	s_mov_b32 s8, s86
	v_mov_b32_e32 v1, v0
	v_mov_b32_e32 v2, v0
	v_mov_b32_e32 v3, v0
	v_mov_b32_e32 v4, v0
	v_mov_b32_e32 v5, v0
	v_mov_b32_e32 v6, v0
	v_mov_b32_e32 v7, v0
	v_mov_b32_e32 v8, v0
	v_mov_b32_e32 v9, v0
	v_mov_b32_e32 v10, v0
	v_mov_b32_e32 v11, v0
	v_mov_b32_e32 v12, v0
	v_mov_b32_e32 v13, v0
	v_mov_b32_e32 v14, v0
	v_mov_b32_e32 v15, v0

; __device__ __forceinline__ unsigned cvt_pk_bf16(float lo, float hi) { unsigned r; asm volatile("v_cvt_pk_bf16_f32 %0, %1, %2" : "=v"(r) : "v"(lo), "v"(hi)); return r; }
; #define GAS __attribute__((address_space(1)))
; __device__ __forceinline__ float bf_lo(unsigned w) { return __uint_as_float(w << 16); }
; __device__ __forceinline__ float bf_hi(unsigned w) { return __uint_as_float(w & 0xffff0000u); }
; __device__ __forceinline__ void spatial_phase(LAS unsigned char* lds, const bf16_t* U, const bf16_t* VT, const float* vsum, const float* vsq, const float* lng, const float* Ws, const float* bs, bf16_t* Y, int c0, int G, int nunits, int ldt) {
;     ...
;             u32x4 oa, ob;
;             oa.x = cvt_pk_bf16(bf_lo(ua.x) * (C[0] + bias), bf_hi(ua.x) * (C[1] + bias)); oa.y = cvt_pk_bf16(bf_lo(ua.y) * (C[2] + bias), bf_hi(ua.y) * (C[3] + bias));
;             oa.z = cvt_pk_bf16(bf_lo(ua.z) * (C[4] + bias), bf_hi(ua.z) * (C[5] + bias)); oa.w = cvt_pk_bf16(bf_lo(ua.w) * (C[6] + bias), bf_hi(ua.w) * (C[7] + bias));
;             ob.x = cvt_pk_bf16(bf_lo(ub.x) * (C[8] + bias), bf_hi(ub.x) * (C[9] + bias)); ob.y = cvt_pk_bf16(bf_lo(ub.y) * (C[10] + bias), bf_hi(ub.y) * (C[11] + bias));
;             ob.z = cvt_pk_bf16(bf_lo(ub.z) * (C[12] + bias), bf_hi(ub.z) * (C[13] + bias)); ob.w = cvt_pk_bf16(bf_lo(ub.w) * (C[14] + bias), bf_hi(ub.w) * (C[15] + bias));
;             *(GAS u32x4*)(Y + off) = oa; *(GAS u32x4*)(Y + off + 8) = ob;
;         }
;         if (un < nunits) {
;             if (!wfixed) { __syncthreads(); SP_WTILE(un & 7); }
.LBB0_258:
	s_waitcnt vmcnt(6)
	s_cmp_eq_u32 s46, 0
	s_cbranch_scc1 .Lsp_w1
	s_waitcnt vmcnt(2)
.Lsp_w1:
	v_lshlrev_b32_e32 v45, 16, v200
	s_nop 7
	v_add_f32_e32 v0, v205, v0
	v_and_b32_e32 v200, 0xffff0000, v200
	v_add_f32_e32 v1, v205, v1
	v_mul_f32_e32 v0, v0, v45
	v_mul_f32_e32 v1, v1, v200
	v_cvt_pk_bf16_f32 v0, v0, v1
	v_lshlrev_b32_e32 v1, 16, v201
	v_add_f32_e32 v2, v205, v2
	v_mul_f32_e32 v1, v2, v1
	v_and_b32_e32 v2, 0xffff0000, v201
	v_add_f32_e32 v3, v205, v3
	v_mul_f32_e32 v2, v3, v2
	v_cvt_pk_bf16_f32 v1, v1, v2
	v_lshlrev_b32_e32 v2, 16, v202
	v_add_f32_e32 v3, v205, v4
	v_mul_f32_e32 v2, v3, v2
	v_and_b32_e32 v3, 0xffff0000, v202
	v_add_f32_e32 v4, v205, v5
	v_mul_f32_e32 v3, v4, v3
	v_cvt_pk_bf16_f32 v2, v2, v3
	v_lshlrev_b32_e32 v3, 16, v203
	v_add_f32_e32 v4, v205, v6
	v_mul_f32_e32 v3, v4, v3
	v_and_b32_e32 v4, 0xffff0000, v203
	v_add_f32_e32 v5, v205, v7
	v_mul_f32_e32 v4, v5, v4
	v_cvt_pk_bf16_f32 v3, v3, v4
	v_lshlrev_b32_e32 v4, 16, v196
	v_add_f32_e32 v5, v205, v8
	v_mul_f32_e32 v4, v5, v4
	v_and_b32_e32 v5, 0xffff0000, v196
	v_add_f32_e32 v6, v205, v9
	v_mul_f32_e32 v5, v6, v5
	v_cvt_pk_bf16_f32 v4, v4, v5
	v_lshlrev_b32_e32 v5, 16, v197
	v_add_f32_e32 v6, v205, v10
	v_mul_f32_e32 v5, v6, v5
	v_and_b32_e32 v6, 0xffff0000, v197
	v_add_f32_e32 v7, v205, v11
	v_mul_f32_e32 v6, v7, v6
	v_cvt_pk_bf16_f32 v5, v5, v6
	v_lshlrev_b32_e32 v6, 16, v198
	v_add_f32_e32 v7, v205, v12
	v_mul_f32_e32 v6, v7, v6
	v_and_b32_e32 v7, 0xffff0000, v198
	v_add_f32_e32 v8, v205, v13
	v_mul_f32_e32 v7, v8, v7
	v_cvt_pk_bf16_f32 v6, v6, v7
	v_lshlrev_b32_e32 v7, 16, v199
	v_add_f32_e32 v8, v205, v14
	v_mul_f32_e32 v7, v8, v7
	v_and_b32_e32 v8, 0xffff0000, v199
	v_add_f32_e32 v9, v205, v15
	v_readlane_b32 s88, v252, 1
	v_mul_f32_e32 v8, v9, v8
	v_readlane_b32 s89, v252, 2
	v_readlane_b32 s90, v252, 3
	v_readlane_b32 s91, v252, 4
	v_cvt_pk_bf16_f32 v7, v7, v8
	s_and_b64 vcc, exec, s[48:49]
	v_readlane_b32 s88, v254, 6
	v_lshl_add_u64 v[8:9], v[206:207], 1, s[90:91]
	s_movk_i32 s89, 0xf0
	global_store_dwordx4 v[8:9], v[0:3], off
	global_store_dwordx4 v[8:9], v[4:7], off offset:16
	s_cbranch_vccz .LBB0_247
	v_readlane_b32 s8, v253, 5
	v_readlane_b32 s9, v253, 6
	s_andn2_b64 vcc, exec, s[8:9]
	s_cbranch_vccnz .LBB0_261
	s_lshl_b32 s0, s87, 7
	s_and_b32 s0, s0, 0x380
	v_lshl_add_u64 v[0:1], s[0:1], 0, v[42:43]
	v_lshlrev_b64 v[0:1], 9, v[0:1]
	v_lshl_add_u64 v[8:9], v[46:47], 0, v[0:1]
	s_barrier
	global_load_dwordx4 v[0:3], v[8:9], off offset:16
	global_load_dwordx4 v[4:7], v[8:9], off
	v_readlane_b32 s8, v254, 41
	v_readlane_b32 s9, v254, 42
	s_waitcnt vmcnt(0)
	s_nop 0
	v_cndmask_b32_e64 v4, v4, 0, s[8:9]
	v_readlane_b32 s8, v254, 43
	v_readlane_b32 s9, v254, 44
	s_nop 1
	v_cndmask_b32_e64 v5, 0, v5, s[8:9]
	v_readlane_b32 s8, v254, 51
	v_readlane_b32 s9, v254, 52
	s_nop 1
	v_cndmask_b32_e64 v6, v6, 0, s[8:9]
	v_readlane_b32 s8, v254, 49
	v_readlane_b32 s9, v254, 50
	s_nop 1
	v_cndmask_b32_e64 v7, v7, 0, s[8:9]
	v_readlane_b32 s8, v254, 45
	v_readlane_b32 s9, v254, 46
	s_nop 1
	v_cndmask_b32_e64 v10, v0, 0, s[8:9]
	v_readlane_b32 s8, v254, 47
	v_readlane_b32 s9, v254, 48
	v_cvt_pk_bf16_f32 v0, v4, v5
	s_nop 1
	v_cndmask_b32_e64 v11, v1, 0, s[8:9]
	v_readlane_b32 s8, v254, 37
	v_readlane_b32 s9, v254, 38
	v_cvt_pk_bf16_f32 v1, v6, v7
	s_nop 1
	v_cndmask_b32_e64 v12, v2, 0, s[8:9]
	v_readlane_b32 s8, v254, 39
	v_readlane_b32 s9, v254, 40
	v_cvt_pk_bf16_f32 v2, v10, v11
	s_nop 1
	v_cndmask_b32_e64 v3, v3, 0, s[8:9]
	v_cvt_pk_bf16_f32 v3, v12, v3
	ds_write_b128 v51, v[0:3]
	global_load_dwordx4 v[0:3], v[8:9], off offset:48
	global_load_dwordx4 v[4:7], v[8:9], off offset:32
	v_readlane_b32 s8, v254, 55
	v_readlane_b32 s9, v254, 56
	s_waitcnt vmcnt(0)
	s_nop 0
	v_cndmask_b32_e64 v4, v4, 0, s[8:9]
	v_readlane_b32 s8, v254, 53
	v_readlane_b32 s9, v254, 54
	s_nop 1
	v_cndmask_b32_e64 v5, v5, 0, s[8:9]
	v_readlane_b32 s8, v254, 57
	v_readlane_b32 s9, v254, 58
	s_nop 1
	v_cndmask_b32_e64 v6, v6, 0, s[8:9]
	v_readlane_b32 s8, v254, 59
	v_readlane_b32 s9, v254, 60
	s_nop 1
	v_cndmask_b32_e64 v7, v7, 0, s[8:9]
	v_readlane_b32 s8, v254, 61
	v_readlane_b32 s9, v254, 62
	s_nop 1
	v_cndmask_b32_e64 v10, v0, 0, s[8:9]
	v_readlane_b32 s8, v254, 63
	v_readlane_b32 s9, v255, 0
	v_cvt_pk_bf16_f32 v0, v4, v5
	s_nop 1
	v_cndmask_b32_e64 v11, v1, 0, s[8:9]
	v_readlane_b32 s8, v255, 1
	v_readlane_b32 s9, v255, 2
	v_cvt_pk_bf16_f32 v1, v6, v7
	s_nop 1
	v_cndmask_b32_e64 v12, v2, 0, s[8:9]
	v_readlane_b32 s8, v255, 3
	v_readlane_b32 s9, v255, 4
	v_cvt_pk_bf16_f32 v2, v10, v11
	s_nop 1
	v_cndmask_b32_e64 v3, v3, 0, s[8:9]
	v_cvt_pk_bf16_f32 v3, v12, v3
	ds_write_b128 v52, v[0:3]
	global_load_dwordx4 v[0:3], v[8:9], off offset:80
	global_load_dwordx4 v[4:7], v[8:9], off offset:64
	v_readlane_b32 s8, v255, 5
	v_readlane_b32 s9, v255, 6
	s_waitcnt vmcnt(0)
	s_nop 0
	v_cndmask_b32_e64 v4, v4, 0, s[8:9]
	v_readlane_b32 s8, v255, 7
	v_readlane_b32 s9, v255, 8
	s_nop 1
	v_cndmask_b32_e64 v5, v5, 0, s[8:9]
	v_readlane_b32 s8, v255, 9
	v_readlane_b32 s9, v255, 10
	s_nop 1
	v_cndmask_b32_e64 v6, v6, 0, s[8:9]
	v_readlane_b32 s8, v255, 11
	v_readlane_b32 s9, v255, 12
	s_nop 1
	v_cndmask_b32_e64 v7, v7, 0, s[8:9]
	v_readlane_b32 s8, v255, 13
	v_readlane_b32 s9, v255, 14
	s_nop 1
	v_cndmask_b32_e64 v10, v0, 0, s[8:9]
	v_readlane_b32 s8, v255, 15
	v_readlane_b32 s9, v255, 16
	v_cvt_pk_bf16_f32 v0, v4, v5
	s_nop 1
	v_cndmask_b32_e64 v11, v1, 0, s[8:9]
	v_readlane_b32 s8, v255, 17
	v_readlane_b32 s9, v255, 18
	v_cvt_pk_bf16_f32 v1, v6, v7
	s_nop 1
	v_cndmask_b32_e64 v12, v2, 0, s[8:9]
	v_readlane_b32 s8, v255, 19
	v_readlane_b32 s9, v255, 20
	v_cvt_pk_bf16_f32 v2, v10, v11
	s_nop 1
	v_cndmask_b32_e64 v3, v3, 0, s[8:9]
	v_cvt_pk_bf16_f32 v3, v12, v3
	ds_write_b128 v53, v[0:3]
	global_load_dwordx4 v[0:3], v[8:9], off offset:112
	global_load_dwordx4 v[4:7], v[8:9], off offset:96
	v_readlane_b32 s8, v255, 21
	v_readlane_b32 s9, v255, 22
	s_waitcnt vmcnt(1)
	v_cndmask_b32_e64 v3, v3, 0, s[4:5]
	s_waitcnt vmcnt(0)
	v_cndmask_b32_e64 v4, v4, 0, s[8:9]
	v_readlane_b32 s8, v255, 23
	v_readlane_b32 s9, v255, 24
	v_cndmask_b32_e64 v5, v5, 0, s[72:73]
	v_cndmask_b32_e64 v7, v7, 0, s[92:93]
	v_cndmask_b32_e64 v6, v6, 0, s[8:9]
	v_cndmask_b32_e64 v8, v0, 0, s[94:95]
	v_cndmask_b32_e64 v9, v1, 0, s[96:97]
	v_cndmask_b32_e64 v10, v2, 0, s[2:3]
	v_cvt_pk_bf16_f32 v0, v4, v5
	v_cvt_pk_bf16_f32 v1, v6, v7
	v_cvt_pk_bf16_f32 v2, v8, v9
	v_cvt_pk_bf16_f32 v3, v10, v3
	ds_write_b128 v54, v[0:3]
.LBB0_261:
	s_waitcnt vmcnt(4)
	v_add_u32_e32 v0, s0, v42
	v_ashrrev_i32_e32 v1, 31, v0
	v_lshl_add_u64 v[0:1], v[0:1], 2, s[38:39]
	global_load_dword v1, v[0:1], off
	s_xor_b32 s8, s78, 1
	v_lshl_add_u32 v2, s8, 10, v55
	ds_read_b128 v[4:7], v2
	ds_read_b128 v[8:11], v2 offset:16
	ds_read_b128 v[12:15], v2 offset:512
	v_lshlrev_b32_e32 v3, 16, v28
	v_and_b32_e32 v34, 0xffff0000, v28
	s_waitcnt lgkmcnt(2)
	v_sub_f32_e32 v3, v3, v4
	v_sub_f32_e32 v4, v34, v5
	v_lshlrev_b32_e32 v35, 16, v29
	s_waitcnt lgkmcnt(0)
	v_mul_f32_e32 v4, v4, v13
	v_mul_f32_e32 v3, v3, v12
	v_and_b32_e32 v36, 0xffff0000, v29
	v_lshlrev_b32_e32 v37, 16, v30
	v_sub_f32_e32 v8, v37, v8
	v_and_b32_e32 v38, 0xffff0000, v30
	v_lshlrev_b32_e32 v39, 16, v31
	v_and_b32_e32 v40, 0xffff0000, v31
	v_lshl_add_u32 v0, s8, 15, v50
	v_and_b32_e32 v34, 0xffff0000, v24
	v_lshlrev_b32_e32 v37, 16, v26
	v_readlane_b32 s9, v253, 51
	s_add_i32 s48, s87, s9
	s_cmp_lt_i32 s48, s50
	s_cselect_b64 s[8:9], -1, 0
	s_and_b64 s[76:77], s[6:7], s[8:9]
	s_waitcnt vmcnt(0)
	v_mul_f32_e32 v12, v1, v4
	v_sub_f32_e32 v4, v35, v6
	v_mul_f32_e32 v4, v4, v14
	v_mul_f32_e32 v13, v1, v4
	v_sub_f32_e32 v4, v36, v7
	v_mul_f32_e32 v4, v4, v15
	v_mul_f32_e32 v14, v1, v4
	ds_read_b128 v[4:7], v2 offset:528
	v_mul_f32_e32 v3, v1, v3
	v_lshlrev_b32_e32 v35, 16, v25
	v_and_b32_e32 v36, 0xffff0000, v25
	s_waitcnt lgkmcnt(0)
	v_mul_f32_e32 v4, v8, v4
	v_mul_f32_e32 v8, v1, v4
	v_sub_f32_e32 v4, v38, v9
	v_mul_f32_e32 v4, v4, v5
	v_mul_f32_e32 v9, v1, v4
	v_sub_f32_e32 v4, v39, v10
	v_mul_f32_e32 v4, v4, v6
	v_mul_f32_e32 v10, v1, v4
	v_sub_f32_e32 v4, v40, v11
	v_mul_f32_e32 v4, v4, v7
	v_mul_f32_e32 v7, v1, v4
	v_cvt_pk_bf16_f32 v4, v3, v12
	v_add_u32_e32 v3, v0, v56
	v_cvt_pk_bf16_f32 v5, v13, v14
	v_cvt_pk_bf16_f32 v6, v8, v9
	v_cvt_pk_bf16_f32 v7, v10, v7
	ds_write_b128 v3, v[4:7] offset:32768
	ds_read_b128 v[4:7], v2 offset:32
	ds_read_b128 v[8:11], v2 offset:48
	ds_read_b128 v[12:15], v2 offset:544
	v_lshlrev_b32_e32 v3, 16, v24
	v_and_b32_e32 v38, 0xffff0000, v26
	s_waitcnt lgkmcnt(2)
	v_sub_f32_e32 v3, v3, v4
	v_sub_f32_e32 v4, v34, v5
	s_waitcnt lgkmcnt(0)
	v_mul_f32_e32 v4, v4, v13
	v_mul_f32_e32 v3, v3, v12
	v_mul_f32_e32 v12, v1, v4
	v_sub_f32_e32 v4, v35, v6
	v_mul_f32_e32 v4, v4, v14
	v_mul_f32_e32 v13, v1, v4
	v_sub_f32_e32 v4, v36, v7
	v_mul_f32_e32 v4, v4, v15
	v_mul_f32_e32 v14, v1, v4
	ds_read_b128 v[4:7], v2 offset:560
	v_sub_f32_e32 v8, v37, v8
	v_lshlrev_b32_e32 v39, 16, v27
	v_and_b32_e32 v40, 0xffff0000, v27
	v_mul_f32_e32 v3, v1, v3
	s_waitcnt lgkmcnt(0)
	v_mul_f32_e32 v4, v8, v4
	v_mul_f32_e32 v8, v1, v4
	v_sub_f32_e32 v4, v38, v9
	v_mul_f32_e32 v4, v4, v5
	v_mul_f32_e32 v9, v1, v4
	v_sub_f32_e32 v4, v39, v10
	v_mul_f32_e32 v4, v4, v6
	v_mul_f32_e32 v10, v1, v4
	v_sub_f32_e32 v4, v40, v11
	v_mul_f32_e32 v4, v4, v7
	v_mul_f32_e32 v7, v1, v4
	v_cvt_pk_bf16_f32 v4, v3, v12
	v_add_u32_e32 v3, v0, v57
	v_cvt_pk_bf16_f32 v5, v13, v14
	v_cvt_pk_bf16_f32 v6, v8, v9
	v_cvt_pk_bf16_f32 v7, v10, v7
	ds_write_b128 v3, v[4:7] offset:32768
	ds_read_b128 v[4:7], v2 offset:64
	ds_read_b128 v[8:11], v2 offset:80
	ds_read_b128 v[12:15], v2 offset:576
	v_lshlrev_b32_e32 v3, 16, v20
	v_and_b32_e32 v34, 0xffff0000, v20
	s_waitcnt lgkmcnt(2)
	v_sub_f32_e32 v3, v3, v4
	v_sub_f32_e32 v4, v34, v5
	v_lshlrev_b32_e32 v35, 16, v21
	s_waitcnt lgkmcnt(0)
	v_mul_f32_e32 v4, v4, v13
	v_mul_f32_e32 v3, v3, v12
	v_mul_f32_e32 v12, v1, v4
	v_sub_f32_e32 v4, v35, v6
	v_and_b32_e32 v36, 0xffff0000, v21
	v_mul_f32_e32 v4, v4, v14
	v_mul_f32_e32 v13, v1, v4
	v_sub_f32_e32 v4, v36, v7
	v_mul_f32_e32 v4, v4, v15
	v_mul_f32_e32 v14, v1, v4
	ds_read_b128 v[4:7], v2 offset:592
	v_lshlrev_b32_e32 v37, 16, v22
	v_sub_f32_e32 v8, v37, v8
	v_and_b32_e32 v38, 0xffff0000, v22
	v_lshlrev_b32_e32 v39, 16, v23
	s_waitcnt lgkmcnt(0)
	v_mul_f32_e32 v4, v8, v4
	v_mul_f32_e32 v8, v1, v4
	v_sub_f32_e32 v4, v38, v9
	v_mul_f32_e32 v4, v4, v5
	v_mul_f32_e32 v9, v1, v4
	v_sub_f32_e32 v4, v39, v10
	v_and_b32_e32 v40, 0xffff0000, v23
	v_mul_f32_e32 v4, v4, v6
	v_mul_f32_e32 v10, v1, v4
	v_sub_f32_e32 v4, v40, v11
	v_mul_f32_e32 v3, v1, v3
	v_mul_f32_e32 v4, v4, v7
	v_mul_f32_e32 v7, v1, v4
	v_cvt_pk_bf16_f32 v4, v3, v12
	v_add_u32_e32 v3, v0, v58
	v_cvt_pk_bf16_f32 v5, v13, v14
	v_cvt_pk_bf16_f32 v6, v8, v9
	v_cvt_pk_bf16_f32 v7, v10, v7
	ds_write_b128 v3, v[4:7] offset:32768
	ds_read_b128 v[4:7], v2 offset:96
	ds_read_b128 v[8:11], v2 offset:112
	ds_read_b128 v[12:15], v2 offset:608
	v_lshlrev_b32_e32 v3, 16, v16
	v_and_b32_e32 v34, 0xffff0000, v16
	s_waitcnt lgkmcnt(2)
	v_sub_f32_e32 v3, v3, v4
	v_lshlrev_b32_e32 v35, 16, v17
	s_waitcnt lgkmcnt(0)
	v_mul_f32_e32 v3, v3, v12
	v_mul_f32_e32 v12, v1, v3
	v_sub_f32_e32 v3, v34, v5
	v_mul_f32_e32 v3, v3, v13
	v_mul_f32_e32 v13, v1, v3
	v_sub_f32_e32 v3, v35, v6
	v_and_b32_e32 v36, 0xffff0000, v17
	v_mul_f32_e32 v3, v3, v14
	v_mul_f32_e32 v6, v1, v3
	v_sub_f32_e32 v3, v36, v7
	v_mul_f32_e32 v3, v3, v15
	v_mul_f32_e32 v7, v1, v3
	ds_read_b128 v[2:5], v2 offset:624
	v_lshlrev_b32_e32 v37, 16, v18
	v_sub_f32_e32 v8, v37, v8
	v_and_b32_e32 v38, 0xffff0000, v18
	v_lshlrev_b32_e32 v39, 16, v19
	s_waitcnt lgkmcnt(0)
	v_mul_f32_e32 v2, v8, v2
	v_mul_f32_e32 v8, v1, v2
	v_sub_f32_e32 v2, v38, v9
	v_mul_f32_e32 v2, v2, v3
	v_mul_f32_e32 v9, v1, v2
	v_sub_f32_e32 v2, v39, v10
	v_and_b32_e32 v40, 0xffff0000, v19
	v_mul_f32_e32 v2, v2, v4
	v_mul_f32_e32 v10, v1, v2
	v_sub_f32_e32 v2, v40, v11
	v_mul_f32_e32 v2, v2, v5
	v_add_u32_e32 v0, v0, v59
	v_mul_f32_e32 v1, v1, v2
	v_cvt_pk_bf16_f32 v2, v12, v13
	v_cvt_pk_bf16_f32 v3, v6, v7
	v_cvt_pk_bf16_f32 v4, v8, v9
	v_cvt_pk_bf16_f32 v5, v10, v1
	ds_write_b128 v0, v[2:5] offset:32768
	s_and_saveexec_b64 s[8:9], s[76:77]
	s_cbranch_execz .LBB0_246
	s_lshl_b32 s0, s48, 4
	s_and_b32 s0, s0, 0xffffff80
	v_add_u32_e32 v0, s0, v33
	v_ashrrev_i32_e32 v1, 31, v0
	v_readlane_b32 s48, v254, 30
	v_lshlrev_b64 v[8:9], 5, v[0:1]
	v_readlane_b32 s49, v254, 31
	s_mov_b32 s0, 0x3a800000
	s_nop 0
	v_lshl_add_u64 v[4:5], s[48:49], 0, v[8:9]
	v_readlane_b32 s48, v254, 35
	global_load_dwordx4 v[0:3], v[4:5], off
	s_nop 0
	global_load_dwordx4 v[4:7], v[4:5], off offset:16
	v_readlane_b32 s49, v254, 36
	s_waitcnt vmcnt(1)
	v_add_f32_e32 v0, v0, v1
	v_lshl_add_u64 v[12:13], s[48:49], 0, v[8:9]
	global_load_dwordx4 v[8:11], v[12:13], off
	s_nop 0
	global_load_dwordx4 v[12:15], v[12:13], off offset:16
	v_add_f32_e32 v1, v2, v3
	s_waitcnt vmcnt(2)
	v_add_f32_e32 v2, v4, v5
	v_add_f32_e32 v3, v6, v7
	v_add_f32_e32 v0, v0, v1
	v_add_f32_e32 v1, v2, v3
	v_add_f32_e32 v0, v0, v1
	v_mul_f32_e32 v0, 0x3a800000, v0
	s_waitcnt vmcnt(1)
	v_add_f32_e32 v4, v8, v9
	v_add_f32_e32 v5, v10, v11
	s_waitcnt vmcnt(0)
	v_add_f32_e32 v6, v12, v13
	v_add_f32_e32 v7, v14, v15
	v_add_f32_e32 v2, v4, v5
	v_add_f32_e32 v3, v6, v7
	v_add_f32_e32 v1, v2, v3
	v_mul_f32_e32 v2, v0, v0
	v_fma_f32 v1, v1, s0, -v2
	v_max_f32_e32 v1, 0, v1
	v_add_f32_e32 v1, 0x3727c5ac, v1
	v_rsq_f32_e32 v1, v1
	v_lshl_add_u32 v2, s78, 10, v68
	ds_write2st64_b32 v2, v0, v1 offset1:2
	s_branch .LBB0_246
